# v86 plus fox_attn prologue de-serialised: q/k-norm gain scalars requested right after the opening barrier, query rows and gain vectors hoisted in front of the max butterflies and window searches
# speedup vs baseline: 1.0028x; 1.0028x over previous
.LBB0_254:
	s_ashr_i32 s44, s85, 5
	s_and_b32 s46, s85, 31
	s_lshl_b32 s47, s46, 8
	s_ashr_i32 s45, s44, 31
	s_add_i32 s42, s47, 0x100
	s_lshl_b64 s[2:3], s[44:45], 15
	v_readlane_b32 s6, v255, 9
	v_readlane_b32 s7, v255, 10
	s_add_u32 s10, s6, s2
	s_mov_b32 s2, 11
	s_addc_u32 s11, s7, s3
	s_ashr_i32 s3, s2, 31
	s_lshl_b64 s[2:3], s[2:3], 3
	s_add_u32 s2, s0, s2
	s_mov_b32 s6, 12
	s_addc_u32 s3, s1, s3
	s_ashr_i32 s7, s6, 31
	s_lshl_b64 s[6:7], s[6:7], 3
	s_add_u32 s20, s0, s6
	s_mov_b32 s6, 13
	s_addc_u32 s21, s1, s7
	s_ashr_i32 s7, s6, 31
	s_lshl_b64 s[6:7], s[6:7], 3
	v_mov_b32_e32 v24, v183
	s_add_u32 s38, s0, s6
	s_addc_u32 s39, s1, s7
	v_lshlrev_b32_e32 v14, 2, v24
	v_readfirstlane_b32 s45, v24
	s_load_dwordx2 s[50:51], s[2:3], 0x0
	s_load_dwordx2 s[52:53], s[20:21], 0x0
	v_cmp_gt_i32_e32 vcc, s42, v14
	s_waitcnt lgkmcnt(0)
	s_barrier
	s_add_u32 s50, s50, s70
	s_addc_u32 s51, s51, s71
	s_add_u32 s52, s52, s70
	s_addc_u32 s53, s53, s71
	v_and_b32_e32 v30, 63, v24
	v_lshlrev_b32_e32 v30, 2, v30
	global_load_dword v31, v30, s[50:51]
	global_load_dword v32, v30, s[52:53]
	s_and_saveexec_b64 s[6:7], vcc
	s_cbranch_execz .LBB0_256
	v_ashrrev_i32_e32 v15, 31, v14
	v_lshl_add_u64 v[2:3], v[14:15], 2, s[10:11]
	flat_load_dwordx4 v[2:5], v[2:3]

.LBB0_266:
	s_or_b64 exec, exec, s[10:11]
	v_and_b32_e32 v185, 63, v24
	s_waitcnt lgkmcnt(0)
	s_add_u32 s40, s6, s70
	s_addc_u32 s41, s7, s71
	v_lshlrev_b32_e32 v0, 2, v185
	s_nop 0
	s_add_u32 s20, s2, s70
	s_addc_u32 s21, s3, s71
	s_nop 0
	s_waitcnt vmcnt(0)
	v_mov_b32_e32 v2, v31
	v_mov_b32_e32 v0, v32
	v_and_b32_e32 v5, 64, v174
	v_add_u32_e32 v5, 64, v5
	v_xor_b32_e32 v6, 1, v174
	v_cmp_lt_i32_e32 vcc, v6, v5
	s_ashr_i32 s54, s45, 6
	s_lshl_b32 s58, s54, 5
	v_cndmask_b32_e32 v6, v174, v6, vcc
	v_lshlrev_b32_e32 v147, 2, v6
	s_add_i32 s58, s58, s47
	s_ashr_i32 s59, s58, 6
	s_ashr_i32 s60, s85, 7
	s_ashr_i32 s61, s60, 31
	s_lshl_b64 s[60:61], s[60:61], 13
	s_lshl_b32 s62, s44, 6
	s_and_b32 s62, s62, 0xc0
	s_ashr_i32 s63, s58, 31
	s_add_u32 s60, s60, s58
	s_addc_u32 s61, s61, s63
	v_and_b32_e32 v84, 31, v24
	v_or_b32_e32 v84, s60, v84
	v_mov_b64_e32 v[86:87], s[26:27]
	v_mad_u64_u32 v[86:87], s[76:77], v84, s18, v[86:87]
	v_mov_b32_e32 v85, 0x1e00
	v_mad_i32_i24 v87, s61, v85, v87
	s_lshl_b32 s62, s62, 1
	s_mov_b32 s63, 0
	v_lshl_add_u64 v[86:87], v[86:87], 0, s[62:63]
	v_lshrrev_b32_e32 v88, 5, v185
	v_lshlrev_b32_e32 v88, 4, v88
	v_mov_b32_e32 v89, v1
	v_lshl_add_u64 v[86:87], v[86:87], 0, v[88:89]
	v_and_b32_e32 v90, 32, v185
	global_load_dwordx4 v[96:99], v[86:87], off offset:2048
	global_load_dwordx4 v[112:115], v90, s[40:41] offset:16
	global_load_dwordx4 v[116:119], v90, s[40:41]
	global_load_dwordx4 v[100:103], v[86:87], off offset:2080
	global_load_dwordx4 v[120:123], v90, s[40:41] offset:80
	global_load_dwordx4 v[124:127], v90, s[40:41] offset:64
	global_load_dwordx4 v[104:107], v[86:87], off offset:2112
	global_load_dwordx4 v[128:131], v90, s[40:41] offset:144
	global_load_dwordx4 v[132:135], v90, s[40:41] offset:128
	global_load_dwordx4 v[108:111], v[86:87], off offset:2144
	global_load_dwordx4 v[136:139], v90, s[40:41] offset:208
	global_load_dwordx4 v[140:143], v90, s[40:41] offset:192
	v_mov_b32_e32 v186, 0
	s_cmp_lt_i32 s59, 1
	s_barrier
	v_and_b32_e32 v3, 0x7fffffff, v2
	ds_bpermute_b32 v3, v147, v3
	v_max_f32_e64 v2, |v2|, |v2|
	v_and_b32_e32 v4, 0x7fffffff, v0
	v_max_f32_e64 v0, |v0|, |v0|
	s_waitcnt lgkmcnt(0)
	v_max_f32_e32 v3, v3, v3
	v_max_f32_e32 v2, v2, v3
	ds_bpermute_b32 v3, v147, v4
	s_waitcnt lgkmcnt(0)
	v_max_f32_e32 v3, v3, v3
	v_max_f32_e32 v0, v0, v3
	v_xor_b32_e32 v3, 2, v174
	v_cmp_lt_i32_e32 vcc, v3, v5
	s_nop 1
	v_cndmask_b32_e32 v3, v174, v3, vcc
	v_lshlrev_b32_e32 v159, 2, v3
	ds_bpermute_b32 v3, v159, v2
	s_waitcnt lgkmcnt(0)
	v_max_f32_e32 v3, v3, v3
	v_max_f32_e32 v2, v2, v3
	ds_bpermute_b32 v3, v159, v0
	s_waitcnt lgkmcnt(0)
	v_max_f32_e32 v3, v3, v3
	v_max_f32_e32 v0, v0, v3
	v_xor_b32_e32 v3, 4, v174
	v_cmp_lt_i32_e32 vcc, v3, v5
	s_nop 1
	v_cndmask_b32_e32 v3, v174, v3, vcc
	v_lshlrev_b32_e32 v184, 2, v3
	ds_bpermute_b32 v3, v184, v2
	s_waitcnt lgkmcnt(0)
	v_max_f32_e32 v3, v3, v3
	v_max_f32_e32 v2, v2, v3
	ds_bpermute_b32 v3, v184, v0
	s_waitcnt lgkmcnt(0)
	v_max_f32_e32 v3, v3, v3
	v_max_f32_e32 v0, v0, v3
	v_xor_b32_e32 v3, 8, v174
	v_cmp_lt_i32_e32 vcc, v3, v5
	s_nop 1
	v_cndmask_b32_e32 v3, v174, v3, vcc
	v_lshlrev_b32_e32 v3, 2, v3
	ds_bpermute_b32 v4, v3, v2
	ds_bpermute_b32 v3, v3, v0
	s_waitcnt lgkmcnt(1)
	v_max_f32_e32 v4, v4, v4
	s_waitcnt lgkmcnt(0)
	v_max_f32_e32 v3, v3, v3
	v_max_f32_e32 v0, v0, v3
	v_xor_b32_e32 v3, 16, v174
	v_cmp_lt_i32_e32 vcc, v3, v5
	v_max_f32_e32 v2, v2, v4
	s_nop 0
	v_cndmask_b32_e32 v3, v174, v3, vcc
	v_lshlrev_b32_e32 v3, 2, v3
	ds_bpermute_b32 v4, v3, v2
	ds_bpermute_b32 v3, v3, v0
	s_waitcnt lgkmcnt(1)
	v_max_f32_e32 v4, v4, v4
	s_waitcnt lgkmcnt(0)
	v_max_f32_e32 v3, v3, v3
	v_max_f32_e32 v0, v0, v3
	v_xor_b32_e32 v3, 32, v174
	v_cmp_lt_i32_e32 vcc, v3, v5
	v_max_f32_e32 v2, v2, v4
	s_nop 0
	v_cndmask_b32_e32 v3, v174, v3, vcc
	v_lshlrev_b32_e32 v187, 2, v3
	ds_bpermute_b32 v3, v187, v2
	s_waitcnt lgkmcnt(0)
	v_max_f32_e32 v3, v3, v3
	v_max_f32_e32 v17, v2, v3
	ds_bpermute_b32 v2, v187, v0
	s_waitcnt lgkmcnt(0)
	v_max_f32_e32 v2, v2, v2
	v_max_f32_e32 v83, v0, v2
	v_mul_f32_e32 v0, 0x41b8aa3b, v17
	v_fmaak_f32 v0, v83, v0, 0x42800000
	s_cbranch_scc1 .LBB0_270
	s_lshl_b32 s2, s58, 2
	s_add_i32 s2, s2, 0
	v_mov_b32_e32 v2, s2
	ds_read_b32 v2, v2
	v_mov_b32_e32 v186, 0
	s_mov_b64 s[2:3], 0
	v_mov_b32_e32 v3, s59

.LBB0_279:
	s_ashr_i32 s2, s85, 7
	s_ashr_i32 s3, s2, 31
	s_lshl_b32 s7, s44, 6
	v_and_b32_e32 v188, 31, v24
	s_lshl_b64 s[38:39], s[2:3], 13
	s_and_b32 s57, s7, 0xc0
	v_or_b32_e32 v189, s58, v188
	s_ashr_i32 s2, s58, 31
	v_lshl_add_u32 v0, v189, 2, 0
	s_add_u32 s55, s38, s58
	ds_read_b32 v16, v0
	v_or_b32_e32 v0, s55, v188
	v_mov_b64_e32 v[2:3], s[26:27]
	s_addc_u32 s56, s39, s2
	v_mad_u64_u32 v[2:3], s[2:3], v0, s18, v[2:3]
	v_mov_b32_e32 v0, 0x1e00
	v_lshrrev_b32_e32 v144, 5, v185
	v_mad_i32_i24 v3, s56, v0, v3
	s_lshl_b32 s80, s57, 1
	v_lshl_add_u64 v[2:3], v[2:3], 0, s[80:81]
	v_lshlrev_b32_e32 v148, 4, v144
	v_mov_b32_e32 v149, v1
	v_lshl_add_u64 v[14:15], v[2:3], 0, v[148:149]
	v_and_b32_e32 v0, 32, v185
	s_add_i32 s2, 0, 0x8000
	v_mov_b32_e32 v149, s2
	v_cmp_eq_u32_e32 vcc, 0, v24
	s_waitcnt vmcnt(0) lgkmcnt(0)
	v_mov_b64_e32 v[2:3], v[96:97]
	v_mov_b64_e32 v[4:5], v[98:99]
	v_mov_b64_e32 v[6:7], v[100:101]
	v_mov_b64_e32 v[8:9], v[102:103]
	v_mov_b64_e32 v[10:11], v[104:105]
	v_mov_b64_e32 v[12:13], v[106:107]
	v_mov_b64_e32 v[18:19], v[108:109]
	v_mov_b64_e32 v[20:21], v[110:111]
	v_mov_b64_e32 v[74:75], v[112:113]
	v_mov_b64_e32 v[76:77], v[114:115]
	v_mov_b64_e32 v[78:79], v[116:117]
	v_mov_b64_e32 v[80:81], v[118:119]
	v_mov_b64_e32 v[58:59], v[120:121]
	v_mov_b64_e32 v[60:61], v[122:123]
	v_mov_b64_e32 v[66:67], v[124:125]
	v_mov_b64_e32 v[68:69], v[126:127]
	v_mov_b64_e32 v[50:51], v[128:129]
	v_mov_b64_e32 v[52:53], v[130:131]
	v_mov_b64_e32 v[54:55], v[132:133]
	v_mov_b64_e32 v[56:57], v[134:135]
	v_mov_b64_e32 v[62:63], v[136:137]
	v_mov_b64_e32 v[64:65], v[138:139]
	v_mov_b64_e32 v[70:71], v[140:141]
	v_mov_b64_e32 v[72:73], v[142:143]
	v_lshlrev_b32_e32 v162, 16, v2
	v_and_b32_e32 v163, 0xffff0000, v2
	v_lshlrev_b32_e32 v160, 16, v3
	v_and_b32_e32 v161, 0xffff0000, v3
	v_pk_mul_f32 v[2:3], v[162:163], v[162:163]
	v_pk_mul_f32 v[36:37], v[160:161], v[160:161]
	v_add_f32_e32 v0, v2, v3
	v_lshlrev_b32_e32 v130, 16, v4
	v_and_b32_e32 v131, 0xffff0000, v4
	v_add_f32_e32 v0, v36, v0
	v_lshlrev_b32_e32 v128, 16, v5
	v_and_b32_e32 v129, 0xffff0000, v5
	v_pk_mul_f32 v[4:5], v[130:131], v[130:131]
	v_add_f32_e32 v0, v37, v0
	v_add_f32_e32 v0, v4, v0
	v_pk_mul_f32 v[34:35], v[128:129], v[128:129]
	v_add_f32_e32 v0, v5, v0
	v_lshlrev_b32_e32 v142, 16, v6
	v_and_b32_e32 v143, 0xffff0000, v6
	v_add_f32_e32 v0, v34, v0
	v_lshlrev_b32_e32 v140, 16, v7
	v_and_b32_e32 v141, 0xffff0000, v7
	v_pk_mul_f32 v[6:7], v[142:143], v[142:143]
	v_add_f32_e32 v0, v35, v0
	v_add_f32_e32 v0, v6, v0
	v_pk_mul_f32 v[32:33], v[140:141], v[140:141]
	v_add_f32_e32 v0, v7, v0
	v_lshlrev_b32_e32 v134, 16, v8
	v_and_b32_e32 v135, 0xffff0000, v8
	v_add_f32_e32 v0, v32, v0
	v_lshlrev_b32_e32 v132, 16, v9
	v_and_b32_e32 v133, 0xffff0000, v9
	v_pk_mul_f32 v[8:9], v[134:135], v[134:135]
	v_add_f32_e32 v0, v33, v0
	v_add_f32_e32 v0, v8, v0
	v_pk_mul_f32 v[30:31], v[132:133], v[132:133]
	v_add_f32_e32 v0, v9, v0
	v_lshlrev_b32_e32 v138, 16, v10
	v_and_b32_e32 v139, 0xffff0000, v10
	v_add_f32_e32 v0, v30, v0
	v_lshlrev_b32_e32 v136, 16, v11
	v_and_b32_e32 v137, 0xffff0000, v11
	v_pk_mul_f32 v[10:11], v[138:139], v[138:139]
	v_add_f32_e32 v0, v31, v0
	v_add_f32_e32 v0, v10, v0
	v_pk_mul_f32 v[28:29], v[136:137], v[136:137]
	v_add_f32_e32 v0, v11, v0
	v_lshlrev_b32_e32 v94, 16, v12
	v_and_b32_e32 v95, 0xffff0000, v12
	v_add_f32_e32 v0, v28, v0
	v_lshlrev_b32_e32 v92, 16, v13
	v_and_b32_e32 v93, 0xffff0000, v13
	v_pk_mul_f32 v[12:13], v[94:95], v[94:95]
	v_add_f32_e32 v0, v29, v0
	v_add_f32_e32 v0, v12, v0
	v_pk_mul_f32 v[26:27], v[92:93], v[92:93]
	v_add_f32_e32 v0, v13, v0
	v_lshlrev_b32_e32 v90, 16, v18
	v_and_b32_e32 v91, 0xffff0000, v18
	v_add_f32_e32 v0, v26, v0
	v_lshlrev_b32_e32 v88, 16, v19
	v_and_b32_e32 v89, 0xffff0000, v19
	v_pk_mul_f32 v[18:19], v[90:91], v[90:91]
	v_add_f32_e32 v0, v27, v0
	v_add_f32_e32 v0, v18, v0
	v_pk_mul_f32 v[22:23], v[88:89], v[88:89]
	v_add_f32_e32 v0, v19, v0
	v_lshlrev_b32_e32 v86, 16, v20
	v_and_b32_e32 v87, 0xffff0000, v20
	v_add_f32_e32 v0, v22, v0
	v_lshlrev_b32_e32 v84, 16, v21
	v_and_b32_e32 v85, 0xffff0000, v21
	v_pk_mul_f32 v[20:21], v[86:87], v[86:87]
	v_add_f32_e32 v0, v23, v0
	v_add_f32_e32 v0, v20, v0
	v_pk_mul_f32 v[14:15], v[84:85], v[84:85]
	v_add_f32_e32 v0, v21, v0
	v_add_f32_e32 v0, v14, v0
	v_and_b32_e32 v6, 7, v24
	v_add_f32_e32 v164, v15, v0
	v_lshlrev_b32_e32 v0, 5, v6
	global_load_dwordx4 v[96:99], v0, s[20:21] offset:16
	global_load_dwordx4 v[100:103], v0, s[20:21]
	ds_bpermute_b32 v165, v187, v164
	s_and_saveexec_b64 s[2:3], vcc
	s_add_i32 s10, 0, 0x22000
	v_mov_b32_e32 v0, s10
	ds_write_b32 v0, v1
	s_or_b64 exec, exec, s[2:3]
	v_sub_u32_e32 v2, s6, v82
	v_add_u32_e32 v7, 6, v2
	s_mov_b32 s2, 0x55555556
	v_mul_hi_i32 v2, v7, s2
	v_ashrrev_i32_e32 v168, 3, v24
	v_lshrrev_b32_e32 v3, 31, v2
	v_ashrrev_i32_e32 v169, 31, v168
	v_add_u32_e32 v190, v2, v3
	v_lshl_add_u64 v[2:3], s[38:39], 0, v[168:169]
	v_mov_b64_e32 v[4:5], s[26:27]
	v_mad_u64_u32 v[4:5], s[2:3], v2, s18, v[4:5]
	v_lshlrev_b32_e32 v0, 3, v6
	v_mad_i32_i24 v5, v3, s18, v5
	v_lshl_add_u64 v[2:3], v[4:5], 0, s[80:81]
	v_lshlrev_b32_e32 v0, 1, v0
	v_add_u32_e32 v169, -1, v190
	v_lshl_add_u64 v[150:151], v[2:3], 0, v[0:1]
	s_or_b32 s60, s6, 3
	v_mad_u64_u32 v[2:3], s[2:3], v169, 3, v[82:83]
	v_cmp_ge_i32_e64 s[46:47], s60, v2
	v_lshlrev_b32_e32 v4, 6, v2
	s_and_saveexec_b64 s[2:3], s[46:47]
	s_cbranch_execz .LBB0_283
	v_mad_i64_i32 v[8:9], s[10:11], v4, s18, v[150:151]
	flat_load_dwordx4 v[104:107], v[8:9] offset:2560
